# a5 + WPREP: all 8 weight loads and 8 gain loads of a tile issued before one wait
# speedup vs baseline: 1.0149x; 1.0149x over previous
.LBB0_76:
	s_mul_i32 s78, s90, s80
	s_add_i32 s78, s78, s89
	v_cmp_ne_u64_e64 s[0:1], 0, v[4:5]
	v_add_u32_e32 v6, s78, v11
	v_cmp_ne_u64_e32 vcc, 0, v[2:3]
	s_barrier
	v_add_u32_e32 v8, v12, v15
	v_mov_b32_e32 v22, 0
	v_mov_b32_e32 v23, 0
	v_mov_b32_e32 v24, 0
	v_mov_b32_e32 v25, 0
	v_mov_b32_e32 v26, 0
	v_mov_b32_e32 v27, 0
	v_mov_b32_e32 v28, 0
	v_mov_b32_e32 v29, 0
	v_mov_b32_e32 v30, 1.0
	v_mov_b32_e32 v31, 1.0
	v_mov_b32_e32 v32, 1.0
	v_mov_b32_e32 v33, 1.0
	v_mov_b32_e32 v34, 1.0
	v_mov_b32_e32 v35, 1.0
	v_mov_b32_e32 v36, 1.0
	v_mov_b32_e32 v37, 1.0
	s_and_saveexec_b64 s[80:81], s[0:1]
	s_cbranch_execz .Lwp_noload
	v_mad_u64_u32 v[38:39], s[82:83], v9, v6, 0
	v_lshl_add_u64 v[38:39], v[38:39], 2, v[4:5]
	v_lshlrev_b32_e32 v40, 5, v9
	v_mov_b32_e32 v41, 0
	global_load_dword v22, v[38:39], off
	v_lshl_add_u64 v[38:39], v[38:39], 0, v[40:41]
	global_load_dword v23, v[38:39], off
	v_lshl_add_u64 v[38:39], v[38:39], 0, v[40:41]
	global_load_dword v24, v[38:39], off
	v_lshl_add_u64 v[38:39], v[38:39], 0, v[40:41]
	global_load_dword v25, v[38:39], off
	v_lshl_add_u64 v[38:39], v[38:39], 0, v[40:41]
	global_load_dword v26, v[38:39], off
	v_lshl_add_u64 v[38:39], v[38:39], 0, v[40:41]
	global_load_dword v27, v[38:39], off
	v_lshl_add_u64 v[38:39], v[38:39], 0, v[40:41]
	global_load_dword v28, v[38:39], off
	v_lshl_add_u64 v[38:39], v[38:39], 0, v[40:41]
	global_load_dword v29, v[38:39], off
	s_and_saveexec_b64 s[82:83], vcc
	s_cbranch_execz .Lwp_nogain
	v_ashrrev_i32_e32 v7, 31, v6
	v_lshl_add_u64 v[42:43], v[6:7], 2, v[2:3]
	global_load_dword v30, v[42:43], off
	global_load_dword v31, v[42:43], off offset:32
	global_load_dword v32, v[42:43], off offset:64
	global_load_dword v33, v[42:43], off offset:96
	global_load_dword v34, v[42:43], off offset:128
	global_load_dword v35, v[42:43], off offset:160
	global_load_dword v36, v[42:43], off offset:192
	global_load_dword v37, v[42:43], off offset:224

.Lwp_noload:
	s_or_b64 exec, exec, s[80:81]
	s_waitcnt vmcnt(0)
	v_mul_f32_e32 v22, v22, v30
	v_mul_f32_e32 v23, v23, v31
	v_mul_f32_e32 v24, v24, v32
	v_mul_f32_e32 v25, v25, v33
	v_mul_f32_e32 v26, v26, v34
	v_mul_f32_e32 v27, v27, v35
	v_mul_f32_e32 v28, v28, v36
	v_mul_f32_e32 v29, v29, v37
	ds_write_b32 v8, v22
	ds_write_b32 v8, v23 offset:2080
	ds_write_b32 v8, v24 offset:4160
	ds_write_b32 v8, v25 offset:6240
	ds_write_b32 v8, v26 offset:8320
	ds_write_b32 v8, v27 offset:10400
	ds_write_b32 v8, v28 offset:12480
	v_mov_b32_e32 v16, v29
	s_branch .LBB0_65
